# s26 + grid barrier: the first workgroup of each XCD to arrive issues an early buffer_wbl2 (pre-drains dirty L2 lines while the others finish), leader's writeback shortened
# speedup vs baseline: 1.0123x; 1.0048x over previous
; __device__ __forceinline__ unsigned xb_ld(unsigned* p)              { return __hip_atomic_load(p, __ATOMIC_RELAXED, __HIP_MEMORY_SCOPE_AGENT); }
; __device__ __forceinline__ unsigned xb_add(unsigned* p, unsigned v) { return __hip_atomic_fetch_add(p, v, __ATOMIC_RELAXED, __HIP_MEMORY_SCOPE_AGENT); }
; #define XB_SPIN(cond, bar) do { unsigned _sp = 0; while (cond) { __builtin_amdgcn_s_sleep(1); \
;     if ((++_sp & 255u) == 0u) { if (xb_ld(&(bar)[XB_TMO])) break; if (_sp > XB_SPIN_CAP) { atomicAdd(&(bar)[XB_TMO], 1u); break; } } } } while (0)
; __device__ __forceinline__ void xcd_barrier(const XcdBarrier& b, const bool t0) {
;     ...
;         const unsigned old = xb_add(&bar[XB_XSUB(b.x)], 1u);
;         const unsigned gen = old / nloc;
;         if (old + 1u == (gen + 1u) * nloc) {
;             __builtin_amdgcn_fence(__ATOMIC_RELEASE, "agent");
;             asm volatile("s_waitcnt vmcnt(0)" ::: "memory");
;             const unsigned og = xb_add(&bar[XB_TOP], 1u);
;             const unsigned tg = og / nx;
;             if (og + 1u == (tg + 1u) * nx) xb_add(&bar[XB_TOPGEN], 1u);
;             else XB_SPIN(xb_ld(&bar[XB_TOPGEN]) == tg, bar);
;             __builtin_amdgcn_fence(__ATOMIC_ACQUIRE, "agent");
;             xb_add(&bar[XB_XGEN(b.x)], 1u);
;             asm volatile("s_waitcnt vmcnt(0)" ::: "memory");
;         } else {
;             XB_SPIN(xb_ld(&bar[XB_XGEN(b.x)]) == gen, bar);
.LBB0_56:
	s_or_b64 exec, exec, s[12:13]
	v_cvt_f32_u32_e32 v4, v2
	s_waitcnt vmcnt(0)
	v_readfirstlane_b32 s0, v3
	v_sub_u32_e32 v3, 0, v2
	v_rcp_iflag_f32_e32 v4, v4
	v_add_u32_e32 v5, s0, v1
	v_mul_f32_e32 v4, 0x4f7ffffe, v4
	v_cvt_u32_f32_e32 v4, v4
	v_mul_lo_u32 v1, v3, v4
	v_mul_hi_u32 v1, v4, v1
	v_add_u32_e32 v1, v4, v1
	v_mul_hi_u32 v1, v5, v1
	v_mul_lo_u32 v3, v1, v2
	v_sub_u32_e32 v3, v5, v3
	v_add_u32_e32 v4, 1, v1
	v_cmp_ge_u32_e32 vcc, v3, v2
	s_nop 1
	v_cndmask_b32_e32 v1, v1, v4, vcc
	v_sub_u32_e32 v4, v3, v2
	v_cndmask_b32_e32 v3, v3, v4, vcc
	v_add_u32_e32 v4, 1, v1
	v_cmp_ge_u32_e32 vcc, v3, v2
	v_add_u32_e32 v3, 1, v5
	s_nop 0
	v_cndmask_b32_e32 v1, v1, v4, vcc
	v_mul_lo_u32 v4, v2, v1
	v_add_u32_e32 v2, v4, v2
	v_cmp_ne_u32_e32 vcc, v3, v2
	s_and_saveexec_b64 s[0:1], vcc
	s_xor_b64 s[10:11], exec, s[0:1]
	s_cbranch_execz .LBB0_70
	v_sub_u32_e32 v0, v2, v3
	v_cmp_eq_u32_e32 vcc, 31, v0
	s_and_saveexec_b64 s[16:17], vcc
	s_cbranch_execz .Lfwb_8
	buffer_wbl2 sc1
.Lfwb_8:
	s_or_b64 exec, exec, s[16:17]
	s_waitcnt lgkmcnt(0)
	v_mov_b32_e32 v0, 0x2000
	global_load_dword v0, v0, s[8:9] offset:1024 sc1
	s_add_u32 s16, s8, 0x2400
	s_addc_u32 s17, s9, 0
	s_waitcnt vmcnt(0)
	v_cmp_eq_u32_e32 vcc, v0, v1
	s_and_saveexec_b64 s[12:13], vcc
	s_cbranch_execz .LBB0_69
	s_add_u32 s14, s6, 0x4200
	s_addc_u32 s15, s7, 0
	s_mov_b32 s0, 1
	s_mov_b64 s[18:19], 0
	v_mov_b32_e32 v0, 0
	s_branch .LBB0_60

; __device__ __forceinline__ unsigned xb_ld(unsigned* p)              { return __hip_atomic_load(p, __ATOMIC_RELAXED, __HIP_MEMORY_SCOPE_AGENT); }
; __device__ __forceinline__ unsigned xb_add(unsigned* p, unsigned v) { return __hip_atomic_fetch_add(p, v, __ATOMIC_RELAXED, __HIP_MEMORY_SCOPE_AGENT); }
; #define XB_SPIN(cond, bar) do { unsigned _sp = 0; while (cond) { __builtin_amdgcn_s_sleep(1); \
;     if ((++_sp & 255u) == 0u) { if (xb_ld(&(bar)[XB_TMO])) break; if (_sp > XB_SPIN_CAP) { atomicAdd(&(bar)[XB_TMO], 1u); break; } } } } while (0)
; __device__ __forceinline__ void xcd_barrier(const XcdBarrier& b, const bool t0) {
;     ...
;         const unsigned old = xb_add(&bar[XB_XSUB(b.x)], 1u);
;         const unsigned gen = old / nloc;
;         if (old + 1u == (gen + 1u) * nloc) {
;             __builtin_amdgcn_fence(__ATOMIC_RELEASE, "agent");
;             asm volatile("s_waitcnt vmcnt(0)" ::: "memory");
;             const unsigned og = xb_add(&bar[XB_TOP], 1u);
;             const unsigned tg = og / nx;
;             if (og + 1u == (tg + 1u) * nx) xb_add(&bar[XB_TOPGEN], 1u);
;             else XB_SPIN(xb_ld(&bar[XB_TOPGEN]) == tg, bar);
;             __builtin_amdgcn_fence(__ATOMIC_ACQUIRE, "agent");
;             xb_add(&bar[XB_XGEN(b.x)], 1u);
;             asm volatile("s_waitcnt vmcnt(0)" ::: "memory");
;         } else {
;             XB_SPIN(xb_ld(&bar[XB_XGEN(b.x)]) == gen, bar);
.LBB0_478:
	s_or_b64 exec, exec, s[12:13]
	v_cvt_f32_u32_e32 v4, v2
	s_waitcnt vmcnt(0)
	v_readfirstlane_b32 s0, v3
	v_sub_u32_e32 v3, 0, v2
	v_rcp_iflag_f32_e32 v4, v4
	v_add_u32_e32 v5, s0, v1
	v_mul_f32_e32 v4, 0x4f7ffffe, v4
	v_cvt_u32_f32_e32 v4, v4
	v_mul_lo_u32 v1, v3, v4
	v_mul_hi_u32 v1, v4, v1
	v_add_u32_e32 v1, v4, v1
	v_mul_hi_u32 v1, v5, v1
	v_mul_lo_u32 v3, v1, v2
	v_sub_u32_e32 v3, v5, v3
	v_add_u32_e32 v4, 1, v1
	v_cmp_ge_u32_e32 vcc, v3, v2
	s_nop 1
	v_cndmask_b32_e32 v1, v1, v4, vcc
	v_sub_u32_e32 v4, v3, v2
	v_cndmask_b32_e32 v3, v3, v4, vcc
	v_add_u32_e32 v4, 1, v1
	v_cmp_ge_u32_e32 vcc, v3, v2
	v_add_u32_e32 v3, 1, v5
	s_nop 0
	v_cndmask_b32_e32 v1, v1, v4, vcc
	v_mul_lo_u32 v4, v2, v1
	v_add_u32_e32 v2, v4, v2
	v_cmp_ne_u32_e32 vcc, v3, v2
	s_and_saveexec_b64 s[0:1], vcc
	s_xor_b64 s[10:11], exec, s[0:1]
	s_cbranch_execz .LBB0_492
	v_sub_u32_e32 v0, v2, v3
	v_cmp_eq_u32_e32 vcc, 31, v0
	s_and_saveexec_b64 s[22:23], vcc
	s_cbranch_execz .Lfwb_5
	buffer_wbl2 sc1
.Lfwb_5:
	s_or_b64 exec, exec, s[22:23]
	s_waitcnt lgkmcnt(0)
	global_load_dword v0, v253, s[8:9] offset:1024 sc1
	s_add_u32 s22, s8, 0x2400
	s_addc_u32 s23, s9, 0
	s_waitcnt vmcnt(0)
	v_cmp_eq_u32_e32 vcc, v0, v1
	s_and_saveexec_b64 s[12:13], vcc
	s_cbranch_execz .LBB0_491
	s_add_u32 s14, s6, 0x4200
	s_addc_u32 s15, s7, 0
	s_mov_b32 s0, 1
	s_mov_b64 s[24:25], 0
	s_branch .LBB0_482

; __device__ __forceinline__ unsigned xb_ld(unsigned* p)              { return __hip_atomic_load(p, __ATOMIC_RELAXED, __HIP_MEMORY_SCOPE_AGENT); }
; __device__ __forceinline__ unsigned xb_add(unsigned* p, unsigned v) { return __hip_atomic_fetch_add(p, v, __ATOMIC_RELAXED, __HIP_MEMORY_SCOPE_AGENT); }
; #define XB_SPIN(cond, bar) do { unsigned _sp = 0; while (cond) { __builtin_amdgcn_s_sleep(1); \
;     if ((++_sp & 255u) == 0u) { if (xb_ld(&(bar)[XB_TMO])) break; if (_sp > XB_SPIN_CAP) { atomicAdd(&(bar)[XB_TMO], 1u); break; } } } } while (0)
; __device__ __forceinline__ void xcd_barrier(const XcdBarrier& b, const bool t0) {
;     ...
;         const unsigned old = xb_add(&bar[XB_XSUB(b.x)], 1u);
;         const unsigned gen = old / nloc;
;         if (old + 1u == (gen + 1u) * nloc) {
;             __builtin_amdgcn_fence(__ATOMIC_RELEASE, "agent");
;             asm volatile("s_waitcnt vmcnt(0)" ::: "memory");
;             const unsigned og = xb_add(&bar[XB_TOP], 1u);
;             const unsigned tg = og / nx;
;             if (og + 1u == (tg + 1u) * nx) xb_add(&bar[XB_TOPGEN], 1u);
;             else XB_SPIN(xb_ld(&bar[XB_TOPGEN]) == tg, bar);
;             __builtin_amdgcn_fence(__ATOMIC_ACQUIRE, "agent");
;             xb_add(&bar[XB_XGEN(b.x)], 1u);
;             asm volatile("s_waitcnt vmcnt(0)" ::: "memory");
;         } else {
;             XB_SPIN(xb_ld(&bar[XB_XGEN(b.x)]) == gen, bar);
.LBB0_558:
	s_or_b64 exec, exec, s[12:13]
	v_cvt_f32_u32_e32 v4, v2
	s_waitcnt vmcnt(0)
	v_readfirstlane_b32 s0, v3
	v_sub_u32_e32 v3, 0, v2
	v_rcp_iflag_f32_e32 v4, v4
	v_add_u32_e32 v5, s0, v1
	v_mul_f32_e32 v4, 0x4f7ffffe, v4
	v_cvt_u32_f32_e32 v4, v4
	v_mul_lo_u32 v1, v3, v4
	v_mul_hi_u32 v1, v4, v1
	v_add_u32_e32 v1, v4, v1
	v_mul_hi_u32 v1, v5, v1
	v_mul_lo_u32 v3, v1, v2
	v_sub_u32_e32 v3, v5, v3
	v_add_u32_e32 v4, 1, v1
	v_cmp_ge_u32_e32 vcc, v3, v2
	s_nop 1
	v_cndmask_b32_e32 v1, v1, v4, vcc
	v_sub_u32_e32 v4, v3, v2
	v_cndmask_b32_e32 v3, v3, v4, vcc
	v_add_u32_e32 v4, 1, v1
	v_cmp_ge_u32_e32 vcc, v3, v2
	v_add_u32_e32 v3, 1, v5
	s_nop 0
	v_cndmask_b32_e32 v1, v1, v4, vcc
	v_mul_lo_u32 v4, v2, v1
	v_add_u32_e32 v2, v4, v2
	v_cmp_ne_u32_e32 vcc, v3, v2
	s_and_saveexec_b64 s[0:1], vcc
	s_xor_b64 s[10:11], exec, s[0:1]
	s_cbranch_execz .LBB0_572
	v_sub_u32_e32 v0, v2, v3
	v_cmp_eq_u32_e32 vcc, 31, v0
	s_and_saveexec_b64 s[20:21], vcc
	s_cbranch_execz .Lfwb_4
	buffer_wbl2 sc1
.Lfwb_4:
	s_or_b64 exec, exec, s[20:21]
	s_waitcnt lgkmcnt(0)
	global_load_dword v0, v253, s[8:9] offset:1024 sc1
	s_add_u32 s20, s8, 0x2400
	s_addc_u32 s21, s9, 0
	s_waitcnt vmcnt(0)
	v_cmp_eq_u32_e32 vcc, v0, v1
	s_and_saveexec_b64 s[12:13], vcc
	s_cbranch_execz .LBB0_571
	s_add_u32 s14, s6, 0x4200
	s_addc_u32 s15, s7, 0
	s_mov_b32 s0, 1
	s_mov_b64 s[22:23], 0
	s_branch .LBB0_562

; __device__ __forceinline__ unsigned xb_ld(unsigned* p)              { return __hip_atomic_load(p, __ATOMIC_RELAXED, __HIP_MEMORY_SCOPE_AGENT); }
; __device__ __forceinline__ unsigned xb_add(unsigned* p, unsigned v) { return __hip_atomic_fetch_add(p, v, __ATOMIC_RELAXED, __HIP_MEMORY_SCOPE_AGENT); }
; #define XB_SPIN(cond, bar) do { unsigned _sp = 0; while (cond) { __builtin_amdgcn_s_sleep(1); \
;     if ((++_sp & 255u) == 0u) { if (xb_ld(&(bar)[XB_TMO])) break; if (_sp > XB_SPIN_CAP) { atomicAdd(&(bar)[XB_TMO], 1u); break; } } } } while (0)
; __device__ __forceinline__ void xcd_barrier(const XcdBarrier& b, const bool t0) {
;     ...
;         const unsigned old = xb_add(&bar[XB_XSUB(b.x)], 1u);
;         const unsigned gen = old / nloc;
;         if (old + 1u == (gen + 1u) * nloc) {
;             __builtin_amdgcn_fence(__ATOMIC_RELEASE, "agent");
;             asm volatile("s_waitcnt vmcnt(0)" ::: "memory");
;             const unsigned og = xb_add(&bar[XB_TOP], 1u);
;             const unsigned tg = og / nx;
;             if (og + 1u == (tg + 1u) * nx) xb_add(&bar[XB_TOPGEN], 1u);
;             else XB_SPIN(xb_ld(&bar[XB_TOPGEN]) == tg, bar);
;             __builtin_amdgcn_fence(__ATOMIC_ACQUIRE, "agent");
;             xb_add(&bar[XB_XGEN(b.x)], 1u);
;             asm volatile("s_waitcnt vmcnt(0)" ::: "memory");
;         } else {
;             XB_SPIN(xb_ld(&bar[XB_XGEN(b.x)]) == gen, bar);
.LBB0_641:
	s_or_b64 exec, exec, s[12:13]
	v_cvt_f32_u32_e32 v4, v2
	s_waitcnt vmcnt(0)
	v_readfirstlane_b32 s0, v3
	v_sub_u32_e32 v3, 0, v2
	v_rcp_iflag_f32_e32 v4, v4
	v_add_u32_e32 v5, s0, v1
	v_mul_f32_e32 v4, 0x4f7ffffe, v4
	v_cvt_u32_f32_e32 v4, v4
	v_mul_lo_u32 v1, v3, v4
	v_mul_hi_u32 v1, v4, v1
	v_add_u32_e32 v1, v4, v1
	v_mul_hi_u32 v1, v5, v1
	v_mul_lo_u32 v3, v1, v2
	v_sub_u32_e32 v3, v5, v3
	v_add_u32_e32 v4, 1, v1
	v_cmp_ge_u32_e32 vcc, v3, v2
	s_nop 1
	v_cndmask_b32_e32 v1, v1, v4, vcc
	v_sub_u32_e32 v4, v3, v2
	v_cndmask_b32_e32 v3, v3, v4, vcc
	v_add_u32_e32 v4, 1, v1
	v_cmp_ge_u32_e32 vcc, v3, v2
	v_add_u32_e32 v3, 1, v5
	s_nop 0
	v_cndmask_b32_e32 v1, v1, v4, vcc
	v_mul_lo_u32 v4, v2, v1
	v_add_u32_e32 v2, v4, v2
	v_cmp_ne_u32_e32 vcc, v3, v2
	s_and_saveexec_b64 s[0:1], vcc
	s_xor_b64 s[10:11], exec, s[0:1]
	s_cbranch_execz .LBB0_655
	v_sub_u32_e32 v0, v2, v3
	v_cmp_eq_u32_e32 vcc, 31, v0
	s_and_saveexec_b64 s[18:19], vcc
	s_cbranch_execz .Lfwb_3
	buffer_wbl2 sc1
.Lfwb_3:
	s_or_b64 exec, exec, s[18:19]
	s_waitcnt lgkmcnt(0)
	global_load_dword v0, v253, s[8:9] offset:1024 sc1
	s_add_u32 s18, s8, 0x2400
	s_addc_u32 s19, s9, 0
	s_waitcnt vmcnt(0)
	v_cmp_eq_u32_e32 vcc, v0, v1
	s_and_saveexec_b64 s[12:13], vcc
	s_cbranch_execz .LBB0_654
	s_add_u32 s14, s6, 0x4200
	s_addc_u32 s15, s7, 0
	s_mov_b32 s0, 1
	s_mov_b64 s[20:21], 0
	s_branch .LBB0_645
